# scan B-DMA hoist kept; GEMM core: second block per CU (blockIdx>=256) delayed by s_sleep 8 at tile start to de-phase co-resident waves
# speedup vs baseline: 1.0020x; 1.0020x over previous
; DI bfr f2bf(float a) { return (bfr)(pack2(a, 0.f) & 0xffffu); }
; #define GA_LOAD(pr_) do { _Pragma("unroll") for (int i = 0; i < 4; ++i) ra[i] = *(const u32x4*)(Ab + (i * 32) * lda + (pr_) * 64); } while (0)
; #define GB_LOAD(kt_) do { const bfr* bk_ = Bb + (kt_) * NB * 32; \
;     _Pragma("unroll") for (int i = 0; i < 4; ++i) rb[i] = *(const u32x4*)(bk_ + (i * 64) * 32); } while (0)
; #define G_STORE(kt_) do { bfr* as_ = S0 + ((kt_) & 1) * GSTAGE; bfr* bs_ = as_ + 128 * 40; \
;     if (apar == ((kt_) & 1)) { _Pragma("unroll") for (int i = 0; i < 4; ++i) *(u32x4*)(as_ + asoff + i * 32 * 40) = ra[i]; } \
;     _Pragma("unroll") for (int i = 0; i < 4; ++i) *(u32x4*)(bs_ + bsoff + i * 64 * 40) = rb[i]; } while (0)
; template <int lda>
; DI void gemm_mainloop(const bfr* __restrict__ A, const bfr* __restrict__ Bt, int NB, int K, int m0, int n0, char* smem, f32x16 (&acc)[2][4]) {
;     ...
;   u32x4 ra[4], rb[4];
;   const int nk = K >> 5;
;   const int arow = tid >> 3, ac8 = tid & 7, apar = ac8 >> 2;
;   const bfr* Ab = A + (m0 + arow) * lda + ac8 * 8;
;   const int asoff = arow * 40 + (ac8 & 3) * 8;
;   const int brow = tid >> 2, bc4 = tid & 3;
;   const bfr* Bb = Bt + (n0 + brow) * 32 + bc4 * 8;
;   const int bsoff = brow * 40 + bc4 * 8;
;     ...
;   GA_LOAD(0);
;   GB_LOAD(0);
;   G_STORE(0);
;   GB_LOAD(1);
;   __syncthreads();
; DI void phase_gemm_in_even(const Params& p, char* smem) {
;     ...
;       int u = t - NT1, gsel = u >> 6, v = u & 63, mt = v >> 2, nt = v & 3;
;       int isv = gsel >> 1, l = gsel & 1;
;       if (!isv) {
;         float* o = p.out + O_MEMK + (size_t)l * 2097152;
;         bfr* kb = p.KB + (size_t)l * 2097152;
;         gemm_tile<1024>(p.MPB, p.WtXk + (size_t)l * 1048576, 1024, 1024, mt * 128, nt * 256, smem,
;                   [=](int row, int col, float v) {
;                     o[(size_t)row * 1024 + col] = v;
;                     kb[(size_t)row * 1024 + col] = f2bf(v);
;                   });
;       } else {
;         float* o = p.out + O_MEMV + (size_t)l * 2097152;
;         bfr* vt = p.VT + (size_t)l * 2097152;
;         gemm_tile<1024>(p.MPB, p.WtXv + (size_t)l * 1048576, 1024, 1024, mt * 128, nt * 256, smem,
.LBB0_123:
	s_lshl_b32 s1, s56, 15
	s_and_b32 s2, s1, 0x200000
	s_lshl_b32 s1, s56, 5
	s_and_b32 s58, s1, 0x780
	s_lshl_b32 s1, s56, 8
	s_and_b32 s0, s56, 0x7fffff80
	s_and_b32 s57, s1, 0x300
	s_cmpk_lg_i32 s0, 0x700
	s_mov_b64 s[0:1], -1
	s_cbranch_scc0 .LBB0_136
	s_add_u32 s0, s14, s2
	s_addc_u32 s1, s15, 0
	s_mov_b32 s59, 0
	s_mov_b64 s[30:31], 0
	s_lshl_b32 s98, s58, 11
	s_add_u32 s98, s8, s98
	s_addc_u32 s99, s9, 0
	s_lshl_b32 s100, s57, 6
	s_add_u32 s100, s0, s100
	s_addc_u32 s101, s1, 0
	v_writelane_b32 v188, s64, 0
	v_writelane_b32 v188, s65, 1
	v_writelane_b32 v188, s66, 2
	v_writelane_b32 v188, s67, 3
	v_writelane_b32 v188, s68, 4
	v_writelane_b32 v188, s69, 5
	v_writelane_b32 v188, s70, 6
	v_writelane_b32 v188, s71, 7
	v_writelane_b32 v188, s72, 8
	v_writelane_b32 v188, s73, 9
	v_writelane_b32 v188, s74, 10
	v_writelane_b32 v188, s75, 11
	v_writelane_b32 v188, s76, 12
	v_writelane_b32 v188, s77, 13
	v_writelane_b32 v188, s78, 14
	v_writelane_b32 v188, s79, 15
	v_lshrrev_b32_e32 v189, 6, v196
	v_and_b32_e32 v190, 63, v196
	v_readfirstlane_b32 s73, v189
	v_lshrrev_b32_e32 v191, 2, v190
	v_bfe_u32 v192, v190, 4, 2
	v_and_b32_e32 v189, 3, v190
	v_xor_b32_e32 v189, v189, v192
	v_lshlrev_b32_e32 v189, 4, v189
	v_lshl_add_u32 v160, v191, 11, v189
	v_add_u32_e32 v162, 0x8000, v160
	v_lshl_add_u32 v163, v191, 6, v189
	v_and_b32_e32 v191, 31, v190
	v_lshrrev_b32_e32 v192, 5, v190
	v_bfe_u32 v189, v190, 2, 2
	v_xor_b32_e32 v189, v189, v192
	v_lshlrev_b32_e32 v189, 4, v189
	v_lshl_add_u32 v180, v191, 6, v189
	s_lshr_b32 s74, s73, 1
	s_lshl_b32 s74, s74, 12
	s_and_b32 s75, s73, 1
	s_lshl_b32 s75, s75, 13
	v_add_u32_e32 v182, s75, v180
	v_add_u32_e32 v180, s74, v180
	v_xor_b32_e32 v183, 32, v182
	v_xor_b32_e32 v181, 32, v180
	s_lshl_b32 s74, s73, 16
	s_add_u32 s64, s98, s74
	s_addc_u32 s65, s99, 0
	s_lshl_b32 s74, s73, 12
	s_add_u32 s66, s100, s74
	s_addc_u32 s67, s101, 0
	s_lshl_b32 s68, s73, 11
	s_lshl_b32 s69, s73, 12
	s_mov_b32 s70, 0
	s_mov_b32 s71, 0
	s_mov_b32 s72, 0
	s_waitcnt lgkmcnt(0)
	s_barrier
	s_mul_i32 s74, s70, 0x6000
	s_add_u32 s75, s74, s68
	s_mov_b32 m0, s75
	s_add_u32 s76, s74, 0x2000
	s_cmp_eq_u32 s70, 2
	s_cselect_b32 s76, 0x10000, s76
	global_load_lds_dwordx4 v160, s[64:65]
	s_add_u32 m0, s75, 0x400
	s_add_u32 s76, s76, s69
	global_load_lds_dwordx4 v162, s[64:65]
	s_mov_b32 m0, s76
	s_add_u32 s64, s64, 64
	s_addc_u32 s65, s65, 0
	global_load_lds_dwordx4 v163, s[66:67]
	global_load_lds_dwordx4 v163, s[66:67] offset:1024
	global_load_lds_dwordx4 v163, s[66:67] offset:2048
	global_load_lds_dwordx4 v163, s[66:67] offset:3072
	s_add_u32 s66, s66, 0x10000
	s_addc_u32 s67, s67, 0
	s_add_u32 s70, s70, 1
	s_cmp_eq_u32 s70, 3
	s_cselect_b32 s70, 0, s70
	s_mul_i32 s74, s70, 0x6000
	s_add_u32 s75, s74, s68
	s_mov_b32 m0, s75
	s_add_u32 s76, s74, 0x2000
	s_cmp_eq_u32 s70, 2
	s_cselect_b32 s76, 0x10000, s76
	global_load_lds_dwordx4 v160, s[64:65]
	s_add_u32 m0, s75, 0x400
	s_add_u32 s76, s76, s69
	global_load_lds_dwordx4 v162, s[64:65]
	s_mov_b32 m0, s76
	s_add_u32 s64, s64, 64
	s_addc_u32 s65, s65, 0
	global_load_lds_dwordx4 v163, s[66:67]
	global_load_lds_dwordx4 v163, s[66:67] offset:1024
	global_load_lds_dwordx4 v163, s[66:67] offset:2048
	global_load_lds_dwordx4 v163, s[66:67] offset:3072
	s_add_u32 s66, s66, 0x10000
	s_addc_u32 s67, s67, 0
	s_add_u32 s70, s70, 1
	s_cmp_eq_u32 s70, 3
	s_cselect_b32 s70, 0, s70
	s_cmp_lt_u32 s46, 0x100
	s_cbranch_scc1 .Lp1v_nostag
	s_sleep 8
.Lp1v_nostag:
	v_mov_b32_e32 v112, 0
	v_mov_b32_e32 v113, 0
	v_mov_b32_e32 v114, 0
	v_mov_b32_e32 v115, 0
	v_mov_b32_e32 v116, 0
	v_mov_b32_e32 v117, 0
	v_mov_b32_e32 v118, 0
	v_mov_b32_e32 v119, 0
	v_mov_b32_e32 v120, 0
	v_mov_b32_e32 v121, 0
	v_mov_b32_e32 v122, 0
	v_mov_b32_e32 v123, 0
	v_mov_b32_e32 v124, 0
	v_mov_b32_e32 v125, 0
	v_mov_b32_e32 v126, 0
	v_mov_b32_e32 v127, 0
	v_mov_b32_e32 v96, 0
	v_mov_b32_e32 v97, 0
	v_mov_b32_e32 v98, 0
	v_mov_b32_e32 v99, 0
	v_mov_b32_e32 v100, 0
	v_mov_b32_e32 v101, 0
	v_mov_b32_e32 v102, 0
	v_mov_b32_e32 v103, 0
	v_mov_b32_e32 v104, 0
	v_mov_b32_e32 v105, 0
	v_mov_b32_e32 v106, 0
	v_mov_b32_e32 v107, 0
	v_mov_b32_e32 v108, 0
	v_mov_b32_e32 v109, 0
	v_mov_b32_e32 v110, 0
	v_mov_b32_e32 v111, 0
	v_mov_b32_e32 v80, 0
	v_mov_b32_e32 v81, 0
	v_mov_b32_e32 v82, 0
	v_mov_b32_e32 v83, 0
	v_mov_b32_e32 v84, 0
	v_mov_b32_e32 v85, 0
	v_mov_b32_e32 v86, 0
	v_mov_b32_e32 v87, 0
	v_mov_b32_e32 v88, 0
	v_mov_b32_e32 v89, 0
	v_mov_b32_e32 v90, 0
	v_mov_b32_e32 v91, 0
	v_mov_b32_e32 v92, 0
	v_mov_b32_e32 v93, 0
	v_mov_b32_e32 v94, 0
	v_mov_b32_e32 v95, 0
	v_mov_b32_e32 v64, 0
	v_mov_b32_e32 v65, 0
	v_mov_b32_e32 v66, 0
	v_mov_b32_e32 v67, 0
	v_mov_b32_e32 v68, 0
	v_mov_b32_e32 v69, 0
	v_mov_b32_e32 v70, 0
	v_mov_b32_e32 v71, 0
	v_mov_b32_e32 v72, 0
	v_mov_b32_e32 v73, 0
	v_mov_b32_e32 v74, 0
	v_mov_b32_e32 v75, 0
	v_mov_b32_e32 v76, 0
	v_mov_b32_e32 v77, 0
	v_mov_b32_e32 v78, 0
	v_mov_b32_e32 v79, 0
	v_mov_b32_e32 v48, 0
	v_mov_b32_e32 v49, 0
	v_mov_b32_e32 v50, 0
	v_mov_b32_e32 v51, 0
	v_mov_b32_e32 v52, 0
	v_mov_b32_e32 v53, 0
	v_mov_b32_e32 v54, 0
	v_mov_b32_e32 v55, 0
	v_mov_b32_e32 v56, 0
	v_mov_b32_e32 v57, 0
	v_mov_b32_e32 v58, 0
	v_mov_b32_e32 v59, 0
	v_mov_b32_e32 v60, 0
	v_mov_b32_e32 v61, 0
	v_mov_b32_e32 v62, 0
	v_mov_b32_e32 v63, 0
	v_mov_b32_e32 v32, 0
	v_mov_b32_e32 v33, 0
	v_mov_b32_e32 v34, 0
	v_mov_b32_e32 v35, 0
	v_mov_b32_e32 v36, 0
	v_mov_b32_e32 v37, 0
	v_mov_b32_e32 v38, 0
	v_mov_b32_e32 v39, 0
	v_mov_b32_e32 v40, 0
	v_mov_b32_e32 v41, 0
	v_mov_b32_e32 v42, 0
	v_mov_b32_e32 v43, 0
	v_mov_b32_e32 v44, 0
	v_mov_b32_e32 v45, 0
	v_mov_b32_e32 v46, 0
	v_mov_b32_e32 v47, 0
	v_mov_b32_e32 v16, 0
	v_mov_b32_e32 v17, 0
	v_mov_b32_e32 v18, 0
	v_mov_b32_e32 v19, 0
	v_mov_b32_e32 v20, 0
	v_mov_b32_e32 v21, 0
	v_mov_b32_e32 v22, 0
	v_mov_b32_e32 v23, 0
	v_mov_b32_e32 v24, 0
	v_mov_b32_e32 v25, 0
	v_mov_b32_e32 v26, 0
	v_mov_b32_e32 v27, 0
	v_mov_b32_e32 v28, 0
	v_mov_b32_e32 v29, 0
	v_mov_b32_e32 v30, 0
	v_mov_b32_e32 v31, 0
	v_mov_b32_e32 v0, 0
	v_mov_b32_e32 v1, 0
	v_mov_b32_e32 v2, 0
	v_mov_b32_e32 v3, 0
	v_mov_b32_e32 v4, 0
	v_mov_b32_e32 v5, 0
	v_mov_b32_e32 v6, 0
	v_mov_b32_e32 v7, 0
	v_mov_b32_e32 v8, 0
	v_mov_b32_e32 v9, 0
	v_mov_b32_e32 v10, 0
	v_mov_b32_e32 v11, 0
	v_mov_b32_e32 v12, 0
	v_mov_b32_e32 v13, 0
	v_mov_b32_e32 v14, 0
	v_mov_b32_e32 v15, 0

; DI bfr f2bf(float a) { return (bfr)(pack2(a, 0.f) & 0xffffu); }
; #define GA_LOAD(pr_) do { _Pragma("unroll") for (int i = 0; i < 4; ++i) ra[i] = *(const u32x4*)(Ab + (i * 32) * lda + (pr_) * 64); } while (0)
; #define GB_LOAD(kt_) do { const bfr* bk_ = Bb + (kt_) * NB * 32; \
;     _Pragma("unroll") for (int i = 0; i < 4; ++i) rb[i] = *(const u32x4*)(bk_ + (i * 64) * 32); } while (0)
; #define G_STORE(kt_) do { bfr* as_ = S0 + ((kt_) & 1) * GSTAGE; bfr* bs_ = as_ + 128 * 40; \
;     if (apar == ((kt_) & 1)) { _Pragma("unroll") for (int i = 0; i < 4; ++i) *(u32x4*)(as_ + asoff + i * 32 * 40) = ra[i]; } \
;     _Pragma("unroll") for (int i = 0; i < 4; ++i) *(u32x4*)(bs_ + bsoff + i * 64 * 40) = rb[i]; } while (0)
; template <int lda>
; DI void gemm_mainloop(const bfr* __restrict__ A, const bfr* __restrict__ Bt, int NB, int K, int m0, int n0, char* smem, f32x16 (&acc)[2][4]) {
;     ...
;   u32x4 ra[4], rb[4];
;   const int nk = K >> 5;
;   const int arow = tid >> 3, ac8 = tid & 7, apar = ac8 >> 2;
;   const bfr* Ab = A + (m0 + arow) * lda + ac8 * 8;
;   const int asoff = arow * 40 + (ac8 & 3) * 8;
;   const int brow = tid >> 2, bc4 = tid & 3;
;   const bfr* Bb = Bt + (n0 + brow) * 32 + bc4 * 8;
;   const int bsoff = brow * 40 + bc4 * 8;
;     ...
;   GA_LOAD(0);
;   GB_LOAD(0);
;   G_STORE(0);
;   GB_LOAD(1);
;   __syncthreads();
; DI void phase_gemm_in_even(const Params& p, char* smem) {
;     ...
;       int u = t - NT1, gsel = u >> 6, v = u & 63, mt = v >> 2, nt = v & 3;
;       int isv = gsel >> 1, l = gsel & 1;
;       if (!isv) {
;         float* o = p.out + O_MEMK + (size_t)l * 2097152;
;         bfr* kb = p.KB + (size_t)l * 2097152;
;         gemm_tile<1024>(p.MPB, p.WtXk + (size_t)l * 1048576, 1024, 1024, mt * 128, nt * 256, smem,
;                   [=](int row, int col, float v) {
;                     o[(size_t)row * 1024 + col] = v;
;                     kb[(size_t)row * 1024 + col] = f2bf(v);
;                   });
.LBB0_136:
	s_and_b64 vcc, exec, s[0:1]
	s_cbranch_vccz .LBB0_146
	s_add_u32 s0, s12, s2
	s_addc_u32 s1, s13, 0
	s_mov_b32 s59, 0
	s_mov_b64 s[30:31], 0
	s_lshl_b32 s98, s58, 11
	s_add_u32 s98, s8, s98
	s_addc_u32 s99, s9, 0
	s_lshl_b32 s100, s57, 6
	s_add_u32 s100, s0, s100
	s_addc_u32 s101, s1, 0
	v_writelane_b32 v188, s64, 0
	v_writelane_b32 v188, s65, 1
	v_writelane_b32 v188, s66, 2
	v_writelane_b32 v188, s67, 3
	v_writelane_b32 v188, s68, 4
	v_writelane_b32 v188, s69, 5
	v_writelane_b32 v188, s70, 6
	v_writelane_b32 v188, s71, 7
	v_writelane_b32 v188, s72, 8
	v_writelane_b32 v188, s73, 9
	v_writelane_b32 v188, s74, 10
	v_writelane_b32 v188, s75, 11
	v_writelane_b32 v188, s76, 12
	v_writelane_b32 v188, s77, 13
	v_writelane_b32 v188, s78, 14
	v_writelane_b32 v188, s79, 15
	v_lshrrev_b32_e32 v189, 6, v196
	v_and_b32_e32 v190, 63, v196
	v_readfirstlane_b32 s73, v189
	v_lshrrev_b32_e32 v191, 2, v190
	v_bfe_u32 v192, v190, 4, 2
	v_and_b32_e32 v189, 3, v190
	v_xor_b32_e32 v189, v189, v192
	v_lshlrev_b32_e32 v189, 4, v189
	v_lshl_add_u32 v160, v191, 11, v189
	v_add_u32_e32 v162, 0x8000, v160
	v_lshl_add_u32 v163, v191, 6, v189
	v_and_b32_e32 v191, 31, v190
	v_lshrrev_b32_e32 v192, 5, v190
	v_bfe_u32 v189, v190, 2, 2
	v_xor_b32_e32 v189, v189, v192
	v_lshlrev_b32_e32 v189, 4, v189
	v_lshl_add_u32 v180, v191, 6, v189
	s_lshr_b32 s74, s73, 1
	s_lshl_b32 s74, s74, 12
	s_and_b32 s75, s73, 1
	s_lshl_b32 s75, s75, 13
	v_add_u32_e32 v182, s75, v180
	v_add_u32_e32 v180, s74, v180
	v_xor_b32_e32 v183, 32, v182
	v_xor_b32_e32 v181, 32, v180
	s_lshl_b32 s74, s73, 16
	s_add_u32 s64, s98, s74
	s_addc_u32 s65, s99, 0
	s_lshl_b32 s74, s73, 12
	s_add_u32 s66, s100, s74
	s_addc_u32 s67, s101, 0
	s_lshl_b32 s68, s73, 11
	s_lshl_b32 s69, s73, 12
	s_mov_b32 s70, 0
	s_mov_b32 s71, 0
	s_mov_b32 s72, 0
	s_waitcnt lgkmcnt(0)
	s_barrier
	s_mul_i32 s74, s70, 0x6000
	s_add_u32 s75, s74, s68
	s_mov_b32 m0, s75
	s_add_u32 s76, s74, 0x2000
	s_cmp_eq_u32 s70, 2
	s_cselect_b32 s76, 0x10000, s76
	global_load_lds_dwordx4 v160, s[64:65]
	s_add_u32 m0, s75, 0x400
	s_add_u32 s76, s76, s69
	global_load_lds_dwordx4 v162, s[64:65]
	s_mov_b32 m0, s76
	s_add_u32 s64, s64, 64
	s_addc_u32 s65, s65, 0
	global_load_lds_dwordx4 v163, s[66:67]
	global_load_lds_dwordx4 v163, s[66:67] offset:1024
	global_load_lds_dwordx4 v163, s[66:67] offset:2048
	global_load_lds_dwordx4 v163, s[66:67] offset:3072
	s_add_u32 s66, s66, 0x10000
	s_addc_u32 s67, s67, 0
	s_add_u32 s70, s70, 1
	s_cmp_eq_u32 s70, 3
	s_cselect_b32 s70, 0, s70
	s_mul_i32 s74, s70, 0x6000
	s_add_u32 s75, s74, s68
	s_mov_b32 m0, s75
	s_add_u32 s76, s74, 0x2000
	s_cmp_eq_u32 s70, 2
	s_cselect_b32 s76, 0x10000, s76
	global_load_lds_dwordx4 v160, s[64:65]
	s_add_u32 m0, s75, 0x400
	s_add_u32 s76, s76, s69
	global_load_lds_dwordx4 v162, s[64:65]
	s_mov_b32 m0, s76
	s_add_u32 s64, s64, 64
	s_addc_u32 s65, s65, 0
	global_load_lds_dwordx4 v163, s[66:67]
	global_load_lds_dwordx4 v163, s[66:67] offset:1024
	global_load_lds_dwordx4 v163, s[66:67] offset:2048
	global_load_lds_dwordx4 v163, s[66:67] offset:3072
	s_add_u32 s66, s66, 0x10000
	s_addc_u32 s67, s67, 0
	s_add_u32 s70, s70, 1
	s_cmp_eq_u32 s70, 3
	s_cselect_b32 s70, 0, s70
	s_cmp_lt_u32 s46, 0x100
	s_cbranch_scc1 .Lp1k_nostag
	s_sleep 8

; #define GA_LOAD(pr_) do { _Pragma("unroll") for (int i = 0; i < 4; ++i) ra[i] = *(const u32x4*)(Ab + (i * 32) * lda + (pr_) * 64); } while (0)
; #define GB_LOAD(kt_) do { const bfr* bk_ = Bb + (kt_) * NB * 32; \
;     _Pragma("unroll") for (int i = 0; i < 4; ++i) rb[i] = *(const u32x4*)(bk_ + (i * 64) * 32); } while (0)
; #define G_STORE(kt_) do { bfr* as_ = S0 + ((kt_) & 1) * GSTAGE; bfr* bs_ = as_ + 128 * 40; \
;     if (apar == ((kt_) & 1)) { _Pragma("unroll") for (int i = 0; i < 4; ++i) *(u32x4*)(as_ + asoff + i * 32 * 40) = ra[i]; } \
;     _Pragma("unroll") for (int i = 0; i < 4; ++i) *(u32x4*)(bs_ + bsoff + i * 64 * 40) = rb[i]; } while (0)
; template <int lda>
; DI void gemm_mainloop(const bfr* __restrict__ A, const bfr* __restrict__ Bt, int NB, int K, int m0, int n0, char* smem, f32x16 (&acc)[2][4]) {
;     ...
;   u32x4 ra[4], rb[4];
;   const int nk = K >> 5;
;   const int arow = tid >> 3, ac8 = tid & 7, apar = ac8 >> 2;
;   const bfr* Ab = A + (m0 + arow) * lda + ac8 * 8;
;   const int asoff = arow * 40 + (ac8 & 3) * 8;
;   const int brow = tid >> 2, bc4 = tid & 3;
;   const bfr* Bb = Bt + (n0 + brow) * 32 + bc4 * 8;
;   const int bsoff = brow * 40 + bc4 * 8;
;     ...
;   GA_LOAD(0);
;   GB_LOAD(0);
;   G_STORE(0);
;   GB_LOAD(1);
;   __syncthreads();
; DI void phase_gemm_in_even(const Params& p, char* smem) {
;     ...
;   for (int t0 = blockIdx.x; t0 < NT1 + NT2; t0 += gridDim.x) {
;     const int t = (t0 < NT1 && (gridDim.x & 7) == 0) ? xcd_tile(t0, 14) : t0;
;     if (t < NT1) {
;       int mt = t / 14, nt = t % 14;
;       bfr* PB = p.PB;
;       gemm_tile<1024>(p.H, p.WtInE, 3712, 1024, mt * 128, nt * 256, smem,
.LBB0_151:
	s_andn2_b64 vcc, exec, s[0:1]
	s_cbranch_vccnz .LBB0_119
	s_mul_hi_i32 s0, s56, 0x92492493
	s_add_i32 s0, s0, s56
	s_lshr_b32 s1, s0, 31
	s_ashr_i32 s0, s0, 3
	s_add_i32 s0, s0, s1
	s_mul_i32 s1, s0, 14
	s_sub_i32 s1, s56, s1
	s_lshl_b32 s56, s0, 7
	s_lshl_b32 s2, s1, 8
	s_mov_b32 s57, 0
	s_mov_b64 s[30:31], 0
	s_lshl_b32 s98, s56, 11
	s_add_u32 s98, s16, s98
	s_addc_u32 s99, s17, 0
	s_lshl_b32 s100, s2, 6
	s_add_u32 s100, s10, s100
	s_addc_u32 s101, s11, 0
	v_writelane_b32 v188, s64, 0
	v_writelane_b32 v188, s65, 1
	v_writelane_b32 v188, s66, 2
	v_writelane_b32 v188, s67, 3
	v_writelane_b32 v188, s68, 4
	v_writelane_b32 v188, s69, 5
	v_writelane_b32 v188, s70, 6
	v_writelane_b32 v188, s71, 7
	v_writelane_b32 v188, s72, 8
	v_writelane_b32 v188, s73, 9
	v_writelane_b32 v188, s74, 10
	v_writelane_b32 v188, s75, 11
	v_writelane_b32 v188, s76, 12
	v_writelane_b32 v188, s77, 13
	v_writelane_b32 v188, s78, 14
	v_writelane_b32 v188, s79, 15
	v_lshrrev_b32_e32 v189, 6, v196
	v_and_b32_e32 v190, 63, v196
	v_readfirstlane_b32 s73, v189
	v_lshrrev_b32_e32 v191, 2, v190
	v_bfe_u32 v192, v190, 4, 2
	v_and_b32_e32 v189, 3, v190
	v_xor_b32_e32 v189, v189, v192
	v_lshlrev_b32_e32 v189, 4, v189
	v_lshl_add_u32 v160, v191, 11, v189
	v_add_u32_e32 v162, 0x8000, v160
	v_lshl_add_u32 v163, v191, 6, v189
	v_and_b32_e32 v191, 31, v190
	v_lshrrev_b32_e32 v192, 5, v190
	v_bfe_u32 v189, v190, 2, 2
	v_xor_b32_e32 v189, v189, v192
	v_lshlrev_b32_e32 v189, 4, v189
	v_lshl_add_u32 v180, v191, 6, v189
	s_lshr_b32 s74, s73, 1
	s_lshl_b32 s74, s74, 12
	s_and_b32 s75, s73, 1
	s_lshl_b32 s75, s75, 13
	v_add_u32_e32 v182, s75, v180
	v_add_u32_e32 v180, s74, v180
	v_xor_b32_e32 v183, 32, v182
	v_xor_b32_e32 v181, 32, v180
	s_lshl_b32 s74, s73, 16
	s_add_u32 s64, s98, s74
	s_addc_u32 s65, s99, 0
	s_lshl_b32 s74, s73, 12
	s_add_u32 s66, s100, s74
	s_addc_u32 s67, s101, 0
	s_lshl_b32 s68, s73, 11
	s_lshl_b32 s69, s73, 12
	s_mov_b32 s70, 0
	s_mov_b32 s71, 0
	s_mov_b32 s72, 0
	s_waitcnt lgkmcnt(0)
	s_barrier
	s_mul_i32 s74, s70, 0x6000
	s_add_u32 s75, s74, s68
	s_mov_b32 m0, s75
	s_add_u32 s76, s74, 0x2000
	s_cmp_eq_u32 s70, 2
	s_cselect_b32 s76, 0x10000, s76
	global_load_lds_dwordx4 v160, s[64:65]
	s_add_u32 m0, s75, 0x400
	s_add_u32 s76, s76, s69
	global_load_lds_dwordx4 v162, s[64:65]
	s_mov_b32 m0, s76
	s_add_u32 s64, s64, 64
	s_addc_u32 s65, s65, 0
	global_load_lds_dwordx4 v163, s[66:67]
	global_load_lds_dwordx4 v163, s[66:67] offset:1024
	global_load_lds_dwordx4 v163, s[66:67] offset:2048
	global_load_lds_dwordx4 v163, s[66:67] offset:3072
	s_add_u32 s66, s66, 0x3a000
	s_addc_u32 s67, s67, 0
	s_add_u32 s70, s70, 1
	s_cmp_eq_u32 s70, 3
	s_cselect_b32 s70, 0, s70
	s_mul_i32 s74, s70, 0x6000
	s_add_u32 s75, s74, s68
	s_mov_b32 m0, s75
	s_add_u32 s76, s74, 0x2000
	s_cmp_eq_u32 s70, 2
	s_cselect_b32 s76, 0x10000, s76
	global_load_lds_dwordx4 v160, s[64:65]
	s_add_u32 m0, s75, 0x400
	s_add_u32 s76, s76, s69
	global_load_lds_dwordx4 v162, s[64:65]
	s_mov_b32 m0, s76
	s_add_u32 s64, s64, 64
	s_addc_u32 s65, s65, 0
	global_load_lds_dwordx4 v163, s[66:67]
	global_load_lds_dwordx4 v163, s[66:67] offset:1024
	global_load_lds_dwordx4 v163, s[66:67] offset:2048
	global_load_lds_dwordx4 v163, s[66:67] offset:3072
	s_add_u32 s66, s66, 0x3a000
	s_addc_u32 s67, s67, 0
	s_add_u32 s70, s70, 1
	s_cmp_eq_u32 s70, 3
	s_cselect_b32 s70, 0, s70
	s_cmp_lt_u32 s46, 0x100
	s_cbranch_scc1 .Lp1e_nostag
	s_sleep 8

; #define GA_LOAD(pr_) do { _Pragma("unroll") for (int i = 0; i < 4; ++i) ra[i] = *(const u32x4*)(Ab + (i * 32) * lda + (pr_) * 64); } while (0)
; #define GB_LOAD(kt_) do { const bfr* bk_ = Bb + (kt_) * NB * 32; \
;     _Pragma("unroll") for (int i = 0; i < 4; ++i) rb[i] = *(const u32x4*)(bk_ + (i * 64) * 32); } while (0)
; #define G_STORE(kt_) do { bfr* as_ = S0 + ((kt_) & 1) * GSTAGE; bfr* bs_ = as_ + 128 * 40; \
;     if (apar == ((kt_) & 1)) { _Pragma("unroll") for (int i = 0; i < 4; ++i) *(u32x4*)(as_ + asoff + i * 32 * 40) = ra[i]; } \
;     _Pragma("unroll") for (int i = 0; i < 4; ++i) *(u32x4*)(bs_ + bsoff + i * 64 * 40) = rb[i]; } while (0)
; template <int lda>
; DI void gemm_mainloop(const bfr* __restrict__ A, const bfr* __restrict__ Bt, int NB, int K, int m0, int n0, char* smem, f32x16 (&acc)[2][4]) {
;     ...
;   u32x4 ra[4], rb[4];
;   const int nk = K >> 5;
;   const int arow = tid >> 3, ac8 = tid & 7, apar = ac8 >> 2;
;   const bfr* Ab = A + (m0 + arow) * lda + ac8 * 8;
;   const int asoff = arow * 40 + (ac8 & 3) * 8;
;   const int brow = tid >> 2, bc4 = tid & 3;
;   const bfr* Bb = Bt + (n0 + brow) * 32 + bc4 * 8;
;   const int bsoff = brow * 40 + bc4 * 8;
;     ...
;   GA_LOAD(0);
;   GB_LOAD(0);
;   G_STORE(0);
;   GB_LOAD(1);
;   __syncthreads();
; template <bool FIRST, bool HAS_H>
; DI void phase_gemm_resid(const Params& p, const bfr* A, const bfr* Wt, const float* gnext, float* ss, char* smem) {
;     ...
;   for (int t0 = blockIdx.x; t0 < 128 * 4; t0 += gridDim.x) {
;     const int t = ((gridDim.x & 7) == 0) ? xcd_tile(t0, 4) : t0;
;     const int mt = t >> 2, nt = t & 3, m0 = mt * 128, n0 = nt * 256;
;     f32x16 acc[2][4];
;     gemm_mainloop<1024>(A, Wt, 1024, 1024, m0, n0, smem, acc);
.LBB0_843:
	s_lshl_b32 s5, s4, 5
	s_and_b32 s40, s5, 0xffffff80
	s_lshl_b32 s4, s4, 8
	s_and_b32 s39, s4, 0x300
	s_mov_b32 s41, 0
	s_mov_b64 s[24:25], 0
	s_lshl_b32 s98, s40, 11
	s_add_u32 s98, s12, s98
	s_addc_u32 s99, s13, 0
	s_lshl_b32 s100, s39, 6
	s_add_u32 s100, s6, s100
	s_addc_u32 s101, s7, 0
	v_writelane_b32 v187, s64, 0
	v_writelane_b32 v187, s65, 1
	v_writelane_b32 v187, s66, 2
	v_writelane_b32 v187, s67, 3
	v_writelane_b32 v187, s68, 4
	v_writelane_b32 v187, s69, 5
	v_writelane_b32 v187, s70, 6
	v_writelane_b32 v187, s71, 7
	v_writelane_b32 v187, s72, 8
	v_writelane_b32 v187, s73, 9
	v_writelane_b32 v187, s74, 10
	v_writelane_b32 v187, s75, 11
	v_writelane_b32 v187, s76, 12
	v_writelane_b32 v187, s77, 13
	v_writelane_b32 v187, s78, 14
	v_writelane_b32 v187, s79, 15
	v_lshrrev_b32_e32 v188, 6, v196
	v_and_b32_e32 v190, 63, v196
	v_readfirstlane_b32 s73, v188
	v_lshrrev_b32_e32 v191, 2, v190
	v_bfe_u32 v192, v190, 4, 2
	v_and_b32_e32 v188, 3, v190
	v_xor_b32_e32 v188, v188, v192
	v_lshlrev_b32_e32 v188, 4, v188
	v_lshl_add_u32 v176, v191, 11, v188
	v_add_u32_e32 v177, 0x8000, v176
	v_lshl_add_u32 v178, v191, 6, v188
	v_and_b32_e32 v191, 31, v190
	v_lshrrev_b32_e32 v192, 5, v190
	v_bfe_u32 v188, v190, 2, 2
	v_xor_b32_e32 v188, v188, v192
	v_lshlrev_b32_e32 v188, 4, v188
	v_lshl_add_u32 v179, v191, 6, v188
	s_lshr_b32 s74, s73, 1
	s_lshl_b32 s74, s74, 12
	s_and_b32 s75, s73, 1
	s_lshl_b32 s75, s75, 13
	v_add_u32_e32 v181, s75, v179
	v_add_u32_e32 v179, s74, v179
	v_xor_b32_e32 v182, 32, v181
	v_xor_b32_e32 v180, 32, v179
	s_lshl_b32 s74, s73, 16
	s_add_u32 s64, s98, s74
	s_addc_u32 s65, s99, 0
	s_lshl_b32 s74, s73, 12
	s_add_u32 s66, s100, s74
	s_addc_u32 s67, s101, 0
	s_lshl_b32 s68, s73, 11
	s_lshl_b32 s69, s73, 12
	s_mov_b32 s70, 0
	s_mov_b32 s71, 0
	s_mov_b32 s72, 0
	s_waitcnt lgkmcnt(0)
	s_barrier
	s_mul_i32 s74, s70, 0x6000
	s_add_u32 s75, s74, s68
	s_mov_b32 m0, s75
	s_add_u32 s76, s74, 0x2000
	s_cmp_eq_u32 s70, 2
	s_cselect_b32 s76, 0x10000, s76
	global_load_lds_dwordx4 v176, s[64:65]
	s_add_u32 m0, s75, 0x400
	s_add_u32 s76, s76, s69
	global_load_lds_dwordx4 v177, s[64:65]
	s_mov_b32 m0, s76
	s_add_u32 s64, s64, 64
	s_addc_u32 s65, s65, 0
	global_load_lds_dwordx4 v178, s[66:67]
	global_load_lds_dwordx4 v178, s[66:67] offset:1024
	global_load_lds_dwordx4 v178, s[66:67] offset:2048
	global_load_lds_dwordx4 v178, s[66:67] offset:3072
	s_add_u32 s66, s66, 0x10000
	s_addc_u32 s67, s67, 0
	s_add_u32 s70, s70, 1
	s_cmp_eq_u32 s70, 3
	s_cselect_b32 s70, 0, s70
	s_mul_i32 s74, s70, 0x6000
	s_add_u32 s75, s74, s68
	s_mov_b32 m0, s75
	s_add_u32 s76, s74, 0x2000
	s_cmp_eq_u32 s70, 2
	s_cselect_b32 s76, 0x10000, s76
	global_load_lds_dwordx4 v176, s[64:65]
	s_add_u32 m0, s75, 0x400
	s_add_u32 s76, s76, s69
	global_load_lds_dwordx4 v177, s[64:65]
	s_mov_b32 m0, s76
	s_add_u32 s64, s64, 64
	s_addc_u32 s65, s65, 0
	global_load_lds_dwordx4 v178, s[66:67]
	global_load_lds_dwordx4 v178, s[66:67] offset:1024
	global_load_lds_dwordx4 v178, s[66:67] offset:2048
	global_load_lds_dwordx4 v178, s[66:67] offset:3072
	s_add_u32 s66, s66, 0x10000
	s_addc_u32 s67, s67, 0
	s_add_u32 s70, s70, 1
	s_cmp_eq_u32 s70, 3
	s_cselect_b32 s70, 0, s70
	s_cmp_lt_u32 s46, 0x100
	s_cbranch_scc1 .Lp6_nostag
	s_sleep 8

; #define GA_LOAD(pr_) do { _Pragma("unroll") for (int i = 0; i < 4; ++i) ra[i] = *(const u32x4*)(Ab + (i * 32) * lda + (pr_) * 64); } while (0)
; #define GB_LOAD(kt_) do { const bfr* bk_ = Bb + (kt_) * NB * 32; \
;     _Pragma("unroll") for (int i = 0; i < 4; ++i) rb[i] = *(const u32x4*)(bk_ + (i * 64) * 32); } while (0)
; #define G_STORE(kt_) do { bfr* as_ = S0 + ((kt_) & 1) * GSTAGE; bfr* bs_ = as_ + 128 * 40; \
;     if (apar == ((kt_) & 1)) { _Pragma("unroll") for (int i = 0; i < 4; ++i) *(u32x4*)(as_ + asoff + i * 32 * 40) = ra[i]; } \
;     _Pragma("unroll") for (int i = 0; i < 4; ++i) *(u32x4*)(bs_ + bsoff + i * 64 * 40) = rb[i]; } while (0)
; template <int lda>
; DI void gemm_mainloop(const bfr* __restrict__ A, const bfr* __restrict__ Bt, int NB, int K, int m0, int n0, char* smem, f32x16 (&acc)[2][4]) {
;     ...
;   u32x4 ra[4], rb[4];
;   const int nk = K >> 5;
;   const int arow = tid >> 3, ac8 = tid & 7, apar = ac8 >> 2;
;   const bfr* Ab = A + (m0 + arow) * lda + ac8 * 8;
;   const int asoff = arow * 40 + (ac8 & 3) * 8;
;   const int brow = tid >> 2, bc4 = tid & 3;
;   const bfr* Bb = Bt + (n0 + brow) * 32 + bc4 * 8;
;   const int bsoff = brow * 40 + bc4 * 8;
;     ...
;   GA_LOAD(0);
;   GB_LOAD(0);
;   G_STORE(0);
;   GB_LOAD(1);
;   __syncthreads();
; DI void phase_gemm_bf16out(const Params& p, const bfr* A, const bfr* Wt, bfr* C, int N, const float* ss, char* smem) {
;     ...
;   for (int t0 = blockIdx.x; t0 < 128 * ntn; t0 += gridDim.x) {
;     const int t = ((gridDim.x & 7) == 0) ? xcd_tile(t0, ntn) : t0;
;     int mt = t / ntn, nt = t % ntn;
;     gemm_tile<1024>(A, Wt, N, 1024, mt * 128, nt * 256, smem,
.LBB0_925:
	s_ashr_i32 s5, s4, 31
	s_lshr_b32 s5, s5, 30
	s_add_i32 s5, s4, s5
	s_and_b32 s6, s5, 0xfffffc
	s_lshl_b32 s5, s5, 5
	s_and_b32 s30, s5, 0xffffff80
	s_sub_i32 s4, s4, s6
	s_lshl_b32 s29, s4, 8
	s_mov_b32 s31, 0
	s_mov_b64 s[6:7], 0
	s_lshl_b32 s98, s30, 11
	s_add_u32 s98, s10, s98
	s_addc_u32 s99, s11, 0
	s_lshl_b32 s100, s29, 6
	s_add_u32 s100, s12, s100
	s_addc_u32 s101, s13, 0
	v_writelane_b32 v187, s64, 0
	v_writelane_b32 v187, s65, 1
	v_writelane_b32 v187, s66, 2
	v_writelane_b32 v187, s67, 3
	v_writelane_b32 v187, s68, 4
	v_writelane_b32 v187, s69, 5
	v_writelane_b32 v187, s70, 6
	v_writelane_b32 v187, s71, 7
	v_writelane_b32 v187, s72, 8
	v_writelane_b32 v187, s73, 9
	v_writelane_b32 v187, s74, 10
	v_writelane_b32 v187, s75, 11
	v_writelane_b32 v187, s76, 12
	v_writelane_b32 v187, s77, 13
	v_writelane_b32 v187, s78, 14
	v_writelane_b32 v187, s79, 15
	v_lshrrev_b32_e32 v188, 6, v196
	v_and_b32_e32 v189, 63, v196
	v_readfirstlane_b32 s73, v188
	v_lshrrev_b32_e32 v190, 2, v189
	v_bfe_u32 v191, v189, 4, 2
	v_and_b32_e32 v188, 3, v189
	v_xor_b32_e32 v188, v188, v191
	v_lshlrev_b32_e32 v188, 4, v188
	v_lshl_add_u32 v176, v190, 11, v188
	v_add_u32_e32 v177, 0x8000, v176
	v_lshl_add_u32 v178, v190, 6, v188
	v_and_b32_e32 v190, 31, v189
	v_lshrrev_b32_e32 v191, 5, v189
	v_bfe_u32 v188, v189, 2, 2
	v_xor_b32_e32 v188, v188, v191
	v_lshlrev_b32_e32 v188, 4, v188
	v_lshl_add_u32 v179, v190, 6, v188
	s_lshr_b32 s74, s73, 1
	s_lshl_b32 s74, s74, 12
	s_and_b32 s75, s73, 1
	s_lshl_b32 s75, s75, 13
	v_add_u32_e32 v181, s75, v179
	v_add_u32_e32 v179, s74, v179
	v_xor_b32_e32 v182, 32, v181
	v_xor_b32_e32 v180, 32, v179
	s_lshl_b32 s74, s73, 16
	s_add_u32 s64, s98, s74
	s_addc_u32 s65, s99, 0
	s_lshl_b32 s74, s73, 12
	s_add_u32 s66, s100, s74
	s_addc_u32 s67, s101, 0
	s_lshl_b32 s68, s73, 11
	s_lshl_b32 s69, s73, 12
	s_mov_b32 s70, 0
	s_mov_b32 s71, 0
	s_mov_b32 s72, 0
	s_waitcnt lgkmcnt(0)
	s_barrier
	s_mul_i32 s74, s70, 0x6000
	s_add_u32 s75, s74, s68
	s_mov_b32 m0, s75
	s_add_u32 s76, s74, 0x2000
	s_cmp_eq_u32 s70, 2
	s_cselect_b32 s76, 0x10000, s76
	global_load_lds_dwordx4 v176, s[64:65]
	s_add_u32 m0, s75, 0x400
	s_add_u32 s76, s76, s69
	global_load_lds_dwordx4 v177, s[64:65]
	s_mov_b32 m0, s76
	s_add_u32 s64, s64, 64
	s_addc_u32 s65, s65, 0
	global_load_lds_dwordx4 v178, s[66:67]
	global_load_lds_dwordx4 v178, s[66:67] offset:1024
	global_load_lds_dwordx4 v178, s[66:67] offset:2048
	global_load_lds_dwordx4 v178, s[66:67] offset:3072
	s_add_u32 s66, s66, 0x10000
	s_addc_u32 s67, s67, 0
	s_add_u32 s70, s70, 1
	s_cmp_eq_u32 s70, 3
	s_cselect_b32 s70, 0, s70
	s_mul_i32 s74, s70, 0x6000
	s_add_u32 s75, s74, s68
	s_mov_b32 m0, s75
	s_add_u32 s76, s74, 0x2000
	s_cmp_eq_u32 s70, 2
	s_cselect_b32 s76, 0x10000, s76
	global_load_lds_dwordx4 v176, s[64:65]
	s_add_u32 m0, s75, 0x400
	s_add_u32 s76, s76, s69
	global_load_lds_dwordx4 v177, s[64:65]
	s_mov_b32 m0, s76
	s_add_u32 s64, s64, 64
	s_addc_u32 s65, s65, 0
	global_load_lds_dwordx4 v178, s[66:67]
	global_load_lds_dwordx4 v178, s[66:67] offset:1024
	global_load_lds_dwordx4 v178, s[66:67] offset:2048
	global_load_lds_dwordx4 v178, s[66:67] offset:3072
	s_add_u32 s66, s66, 0x10000
	s_addc_u32 s67, s67, 0
	s_add_u32 s70, s70, 1
	s_cmp_eq_u32 s70, 3
	s_cselect_b32 s70, 0, s70
	s_cmp_lt_u32 s46, 0x100
	s_cbranch_scc1 .Lp8_nostag
	s_sleep 8

; #define GA_LOAD(pr_) do { _Pragma("unroll") for (int i = 0; i < 4; ++i) ra[i] = *(const u32x4*)(Ab + (i * 32) * lda + (pr_) * 64); } while (0)
; #define GB_LOAD(kt_) do { const bfr* bk_ = Bb + (kt_) * NB * 32; \
;     _Pragma("unroll") for (int i = 0; i < 4; ++i) rb[i] = *(const u32x4*)(bk_ + (i * 64) * 32); } while (0)
; #define G_STORE(kt_) do { bfr* as_ = S0 + ((kt_) & 1) * GSTAGE; bfr* bs_ = as_ + 128 * 40; \
;     if (apar == ((kt_) & 1)) { _Pragma("unroll") for (int i = 0; i < 4; ++i) *(u32x4*)(as_ + asoff + i * 32 * 40) = ra[i]; } \
;     _Pragma("unroll") for (int i = 0; i < 4; ++i) *(u32x4*)(bs_ + bsoff + i * 64 * 40) = rb[i]; } while (0)
; template <int lda>
; DI void gemm_mainloop(const bfr* __restrict__ A, const bfr* __restrict__ Bt, int NB, int K, int m0, int n0, char* smem, f32x16 (&acc)[2][4]) {
;     ...
;   u32x4 ra[4], rb[4];
;   const int nk = K >> 5;
;   const int arow = tid >> 3, ac8 = tid & 7, apar = ac8 >> 2;
;   const bfr* Ab = A + (m0 + arow) * lda + ac8 * 8;
;   const int asoff = arow * 40 + (ac8 & 3) * 8;
;   const int brow = tid >> 2, bc4 = tid & 3;
;   const bfr* Bb = Bt + (n0 + brow) * 32 + bc4 * 8;
;   const int bsoff = brow * 40 + bc4 * 8;
;     ...
;   GA_LOAD(0);
;   GB_LOAD(0);
;   G_STORE(0);
;   GB_LOAD(1);
;   __syncthreads();
; template <bool FIRST, bool HAS_H>
; DI void phase_gemm_resid(const Params& p, const bfr* A, const bfr* Wt, const float* gnext, float* ss, char* smem) {
;     ...
;   for (int t0 = blockIdx.x; t0 < 128 * 4; t0 += gridDim.x) {
;     const int t = ((gridDim.x & 7) == 0) ? xcd_tile(t0, 4) : t0;
;     const int mt = t >> 2, nt = t & 3, m0 = mt * 128, n0 = nt * 256;
;     f32x16 acc[2][4];
;     gemm_mainloop<1024>(A, Wt, 1024, 1024, m0, n0, smem, acc);
.LBB0_1099:
	s_lshl_b32 s5, s4, 5
	s_and_b32 s36, s5, 0xffffff80
	s_lshl_b32 s4, s4, 8
	s_and_b32 s33, s4, 0x300
	s_mov_b32 s37, 0
	s_mov_b64 s[20:21], 0
	s_lshl_b32 s98, s36, 11
	s_add_u32 s98, s2, s98
	s_addc_u32 s99, s3, 0
	s_lshl_b32 s100, s33, 6
	s_add_u32 s100, s8, s100
	s_addc_u32 s101, s9, 0
	v_writelane_b32 v187, s64, 0
	v_writelane_b32 v187, s65, 1
	v_writelane_b32 v187, s66, 2
	v_writelane_b32 v187, s67, 3
	v_writelane_b32 v187, s68, 4
	v_writelane_b32 v187, s69, 5
	v_writelane_b32 v187, s70, 6
	v_writelane_b32 v187, s71, 7
	v_writelane_b32 v187, s72, 8
	v_writelane_b32 v187, s73, 9
	v_writelane_b32 v187, s74, 10
	v_writelane_b32 v187, s75, 11
	v_writelane_b32 v187, s76, 12
	v_writelane_b32 v187, s77, 13
	v_writelane_b32 v187, s78, 14
	v_writelane_b32 v187, s79, 15
	v_lshrrev_b32_e32 v188, 6, v196
	v_and_b32_e32 v189, 63, v196
	v_readfirstlane_b32 s73, v188
	v_lshrrev_b32_e32 v190, 2, v189
	v_bfe_u32 v191, v189, 4, 2
	v_and_b32_e32 v188, 3, v189
	v_xor_b32_e32 v188, v188, v191
	v_lshlrev_b32_e32 v188, 4, v188
	v_lshl_add_u32 v176, v190, 11, v188
	v_add_u32_e32 v177, 0x8000, v176
	v_lshl_add_u32 v178, v190, 6, v188
	v_and_b32_e32 v190, 31, v189
	v_lshrrev_b32_e32 v191, 5, v189
	v_bfe_u32 v188, v189, 2, 2
	v_xor_b32_e32 v188, v188, v191
	v_lshlrev_b32_e32 v188, 4, v188
	v_lshl_add_u32 v179, v190, 6, v188
	s_lshr_b32 s74, s73, 1
	s_lshl_b32 s74, s74, 12
	s_and_b32 s75, s73, 1
	s_lshl_b32 s75, s75, 13
	v_add_u32_e32 v181, s75, v179
	v_add_u32_e32 v179, s74, v179
	v_xor_b32_e32 v182, 32, v181
	v_xor_b32_e32 v180, 32, v179
	s_lshl_b32 s74, s73, 16
	s_add_u32 s64, s98, s74
	s_addc_u32 s65, s99, 0
	s_lshl_b32 s74, s73, 12
	s_add_u32 s66, s100, s74
	s_addc_u32 s67, s101, 0
	s_lshl_b32 s68, s73, 11
	s_lshl_b32 s69, s73, 12
	s_mov_b32 s70, 0
	s_mov_b32 s71, 0
	s_mov_b32 s72, 0
	s_waitcnt lgkmcnt(0)
	s_barrier
	s_mul_i32 s74, s70, 0x6000
	s_add_u32 s75, s74, s68
	s_mov_b32 m0, s75
	s_add_u32 s76, s74, 0x2000
	s_cmp_eq_u32 s70, 2
	s_cselect_b32 s76, 0x10000, s76
	global_load_lds_dwordx4 v176, s[64:65]
	s_add_u32 m0, s75, 0x400
	s_add_u32 s76, s76, s69
	global_load_lds_dwordx4 v177, s[64:65]
	s_mov_b32 m0, s76
	s_add_u32 s64, s64, 64
	s_addc_u32 s65, s65, 0
	global_load_lds_dwordx4 v178, s[66:67]
	global_load_lds_dwordx4 v178, s[66:67] offset:1024
	global_load_lds_dwordx4 v178, s[66:67] offset:2048
	global_load_lds_dwordx4 v178, s[66:67] offset:3072
	s_add_u32 s66, s66, 0x10000
	s_addc_u32 s67, s67, 0
	s_add_u32 s70, s70, 1
	s_cmp_eq_u32 s70, 3
	s_cselect_b32 s70, 0, s70
	s_mul_i32 s74, s70, 0x6000
	s_add_u32 s75, s74, s68
	s_mov_b32 m0, s75
	s_add_u32 s76, s74, 0x2000
	s_cmp_eq_u32 s70, 2
	s_cselect_b32 s76, 0x10000, s76
	global_load_lds_dwordx4 v176, s[64:65]
	s_add_u32 m0, s75, 0x400
	s_add_u32 s76, s76, s69
	global_load_lds_dwordx4 v177, s[64:65]
	s_mov_b32 m0, s76
	s_add_u32 s64, s64, 64
	s_addc_u32 s65, s65, 0
	global_load_lds_dwordx4 v178, s[66:67]
	global_load_lds_dwordx4 v178, s[66:67] offset:1024
	global_load_lds_dwordx4 v178, s[66:67] offset:2048
	global_load_lds_dwordx4 v178, s[66:67] offset:3072
	s_add_u32 s66, s66, 0x10000
	s_addc_u32 s67, s67, 0
	s_add_u32 s70, s70, 1
	s_cmp_eq_u32 s70, 3
	s_cselect_b32 s70, 0, s70
	s_cmp_lt_u32 s46, 0x100
	s_cbranch_scc1 .Lp10_nostag
	s_sleep 8

; #define GA_LOAD(pr_) do { _Pragma("unroll") for (int i = 0; i < 4; ++i) ra[i] = *(const u32x4*)(Ab + (i * 32) * lda + (pr_) * 64); } while (0)
; #define GB_LOAD(kt_) do { const bfr* bk_ = Bb + (kt_) * NB * 32; \
;     _Pragma("unroll") for (int i = 0; i < 4; ++i) rb[i] = *(const u32x4*)(bk_ + (i * 64) * 32); } while (0)
; #define G_STORE(kt_) do { bfr* as_ = S0 + ((kt_) & 1) * GSTAGE; bfr* bs_ = as_ + 128 * 40; \
;     if (apar == ((kt_) & 1)) { _Pragma("unroll") for (int i = 0; i < 4; ++i) *(u32x4*)(as_ + asoff + i * 32 * 40) = ra[i]; } \
;     _Pragma("unroll") for (int i = 0; i < 4; ++i) *(u32x4*)(bs_ + bsoff + i * 64 * 40) = rb[i]; } while (0)
; template <int lda>
; DI void gemm_mainloop(const bfr* __restrict__ A, const bfr* __restrict__ Bt, int NB, int K, int m0, int n0, char* smem, f32x16 (&acc)[2][4]) {
;     ...
;   u32x4 ra[4], rb[4];
;   const int nk = K >> 5;
;   const int arow = tid >> 3, ac8 = tid & 7, apar = ac8 >> 2;
;   const bfr* Ab = A + (m0 + arow) * lda + ac8 * 8;
;   const int asoff = arow * 40 + (ac8 & 3) * 8;
;   const int brow = tid >> 2, bc4 = tid & 3;
;   const bfr* Bb = Bt + (n0 + brow) * 32 + bc4 * 8;
;   const int bsoff = brow * 40 + bc4 * 8;
;     ...
;   GA_LOAD(0);
;   GB_LOAD(0);
;   G_STORE(0);
;   GB_LOAD(1);
;   __syncthreads();
; DI void phase_gemm_bf16out(const Params& p, const bfr* A, const bfr* Wt, bfr* C, int N, const float* ss, char* smem) {
;     ...
;   for (int t0 = blockIdx.x; t0 < 128 * ntn; t0 += gridDim.x) {
;     const int t = ((gridDim.x & 7) == 0) ? xcd_tile(t0, ntn) : t0;
;     int mt = t / ntn, nt = t % ntn;
;     gemm_tile<1024>(A, Wt, N, 1024, mt * 128, nt * 256, smem,
.LBB0_1181:
	s_ashr_i32 s5, s4, 31
	s_lshr_b32 s5, s5, 29
	s_add_i32 s5, s4, s5
	s_and_b32 s18, s5, 0xfffff8
	s_lshl_b32 s5, s5, 4
	s_and_b32 s30, s5, 0xffffff80
	s_sub_i32 s4, s4, s18
	s_lshl_b32 s29, s4, 8
	s_mov_b32 s31, 0
	s_mov_b64 s[18:19], 0
	s_lshl_b32 s98, s30, 11
	s_add_u32 s98, s10, s98
	s_addc_u32 s99, s11, 0
	s_lshl_b32 s100, s29, 6
	s_add_u32 s100, s12, s100
	s_addc_u32 s101, s13, 0
	v_writelane_b32 v187, s64, 0
	v_writelane_b32 v187, s65, 1
	v_writelane_b32 v187, s66, 2
	v_writelane_b32 v187, s67, 3
	v_writelane_b32 v187, s68, 4
	v_writelane_b32 v187, s69, 5
	v_writelane_b32 v187, s70, 6
	v_writelane_b32 v187, s71, 7
	v_writelane_b32 v187, s72, 8
	v_writelane_b32 v187, s73, 9
	v_writelane_b32 v187, s74, 10
	v_writelane_b32 v187, s75, 11
	v_writelane_b32 v187, s76, 12
	v_writelane_b32 v187, s77, 13
	v_writelane_b32 v187, s78, 14
	v_writelane_b32 v187, s79, 15
	v_lshrrev_b32_e32 v188, 6, v196
	v_and_b32_e32 v189, 63, v196
	v_readfirstlane_b32 s73, v188
	v_lshrrev_b32_e32 v190, 2, v189
	v_bfe_u32 v191, v189, 4, 2
	v_and_b32_e32 v188, 3, v189
	v_xor_b32_e32 v188, v188, v191
	v_lshlrev_b32_e32 v188, 4, v188
	v_lshl_add_u32 v176, v190, 11, v188
	v_add_u32_e32 v177, 0x8000, v176
	v_lshl_add_u32 v178, v190, 6, v188
	v_and_b32_e32 v190, 31, v189
	v_lshrrev_b32_e32 v191, 5, v189
	v_bfe_u32 v188, v189, 2, 2
	v_xor_b32_e32 v188, v188, v191
	v_lshlrev_b32_e32 v188, 4, v188
	v_lshl_add_u32 v179, v190, 6, v188
	s_lshr_b32 s74, s73, 1
	s_lshl_b32 s74, s74, 12
	s_and_b32 s75, s73, 1
	s_lshl_b32 s75, s75, 13
	v_add_u32_e32 v181, s75, v179
	v_add_u32_e32 v179, s74, v179
	v_xor_b32_e32 v182, 32, v181
	v_xor_b32_e32 v180, 32, v179
	s_lshl_b32 s74, s73, 16
	s_add_u32 s64, s98, s74
	s_addc_u32 s65, s99, 0
	s_lshl_b32 s74, s73, 12
	s_add_u32 s66, s100, s74
	s_addc_u32 s67, s101, 0
	s_lshl_b32 s68, s73, 11
	s_lshl_b32 s69, s73, 12
	s_mov_b32 s70, 0
	s_mov_b32 s71, 0
	s_mov_b32 s72, 0
	s_waitcnt lgkmcnt(0)
	s_barrier
	s_mul_i32 s74, s70, 0x6000
	s_add_u32 s75, s74, s68
	s_mov_b32 m0, s75
	s_add_u32 s76, s74, 0x2000
	s_cmp_eq_u32 s70, 2
	s_cselect_b32 s76, 0x10000, s76
	global_load_lds_dwordx4 v176, s[64:65]
	s_add_u32 m0, s75, 0x400
	s_add_u32 s76, s76, s69
	global_load_lds_dwordx4 v177, s[64:65]
	s_mov_b32 m0, s76
	s_add_u32 s64, s64, 64
	s_addc_u32 s65, s65, 0
	global_load_lds_dwordx4 v178, s[66:67]
	global_load_lds_dwordx4 v178, s[66:67] offset:1024
	global_load_lds_dwordx4 v178, s[66:67] offset:2048
	global_load_lds_dwordx4 v178, s[66:67] offset:3072
	s_add_u32 s66, s66, 0x20000
	s_addc_u32 s67, s67, 0
	s_add_u32 s70, s70, 1
	s_cmp_eq_u32 s70, 3
	s_cselect_b32 s70, 0, s70
	s_mul_i32 s74, s70, 0x6000
	s_add_u32 s75, s74, s68
	s_mov_b32 m0, s75
	s_add_u32 s76, s74, 0x2000
	s_cmp_eq_u32 s70, 2
	s_cselect_b32 s76, 0x10000, s76
	global_load_lds_dwordx4 v176, s[64:65]
	s_add_u32 m0, s75, 0x400
	s_add_u32 s76, s76, s69
	global_load_lds_dwordx4 v177, s[64:65]
	s_mov_b32 m0, s76
	s_add_u32 s64, s64, 64
	s_addc_u32 s65, s65, 0
	global_load_lds_dwordx4 v178, s[66:67]
	global_load_lds_dwordx4 v178, s[66:67] offset:1024
	global_load_lds_dwordx4 v178, s[66:67] offset:2048
	global_load_lds_dwordx4 v178, s[66:67] offset:3072
	s_add_u32 s66, s66, 0x20000
	s_addc_u32 s67, s67, 0
	s_add_u32 s70, s70, 1
	s_cmp_eq_u32 s70, 3
	s_cselect_b32 s70, 0, s70
	s_cmp_lt_u32 s46, 0x100
	s_cbranch_scc1 .Lp12_nostag
	s_sleep 8

; #define GA_LOAD(pr_) do { _Pragma("unroll") for (int i = 0; i < 4; ++i) ra[i] = *(const u32x4*)(Ab + (i * 32) * lda + (pr_) * 64); } while (0)
; #define GB_LOAD(kt_) do { const bfr* bk_ = Bb + (kt_) * NB * 32; \
;     _Pragma("unroll") for (int i = 0; i < 4; ++i) rb[i] = *(const u32x4*)(bk_ + (i * 64) * 32); } while (0)
; #define G_STORE(kt_) do { bfr* as_ = S0 + ((kt_) & 1) * GSTAGE; bfr* bs_ = as_ + 128 * 40; \
;     if (apar == ((kt_) & 1)) { _Pragma("unroll") for (int i = 0; i < 4; ++i) *(u32x4*)(as_ + asoff + i * 32 * 40) = ra[i]; } \
;     _Pragma("unroll") for (int i = 0; i < 4; ++i) *(u32x4*)(bs_ + bsoff + i * 64 * 40) = rb[i]; } while (0)
; template <int lda>
; DI void gemm_mainloop(const bfr* __restrict__ A, const bfr* __restrict__ Bt, int NB, int K, int m0, int n0, char* smem, f32x16 (&acc)[2][4]) {
;     ...
;   u32x4 ra[4], rb[4];
;   const int nk = K >> 5;
;   const int arow = tid >> 3, ac8 = tid & 7, apar = ac8 >> 2;
;   const bfr* Ab = A + (m0 + arow) * lda + ac8 * 8;
;   const int asoff = arow * 40 + (ac8 & 3) * 8;
;   const int brow = tid >> 2, bc4 = tid & 3;
;   const bfr* Bb = Bt + (n0 + brow) * 32 + bc4 * 8;
;   const int bsoff = brow * 40 + bc4 * 8;
;     ...
;   GA_LOAD(0);
;   GB_LOAD(0);
;   G_STORE(0);
;   GB_LOAD(1);
;   __syncthreads();
; DI void phase_gemm_bf16out(const Params& p, const bfr* A, const bfr* Wt, bfr* C, int N, const float* ss, char* smem) {
;     ...
;   for (int t0 = blockIdx.x; t0 < 128 * ntn; t0 += gridDim.x) {
;     const int t = ((gridDim.x & 7) == 0) ? xcd_tile(t0, ntn) : t0;
;     int mt = t / ntn, nt = t % ntn;
;     gemm_tile<1024>(A, Wt, N, 1024, mt * 128, nt * 256, smem,
.LBB0_1548:
	s_ashr_i32 s5, s4, 31
	s_lshr_b32 s5, s5, 30
	s_add_i32 s5, s4, s5
	s_and_b32 s20, s5, 0xfffffc
	s_lshl_b32 s5, s5, 5
	s_and_b32 s33, s5, 0xffffff80
	s_sub_i32 s4, s4, s20
	s_lshl_b32 s31, s4, 8
	s_mov_b32 s36, 0
	s_mov_b64 s[20:21], 0
	s_lshl_b32 s98, s33, 11
	s_add_u32 s98, s10, s98
	s_addc_u32 s99, s11, 0
	s_lshl_b32 s100, s31, 6
	s_add_u32 s100, s14, s100
	s_addc_u32 s101, s15, 0
	v_writelane_b32 v187, s64, 0
	v_writelane_b32 v187, s65, 1
	v_writelane_b32 v187, s66, 2
	v_writelane_b32 v187, s67, 3
	v_writelane_b32 v187, s68, 4
	v_writelane_b32 v187, s69, 5
	v_writelane_b32 v187, s70, 6
	v_writelane_b32 v187, s71, 7
	v_writelane_b32 v187, s72, 8
	v_writelane_b32 v187, s73, 9
	v_writelane_b32 v187, s74, 10
	v_writelane_b32 v187, s75, 11
	v_writelane_b32 v187, s76, 12
	v_writelane_b32 v187, s77, 13
	v_writelane_b32 v187, s78, 14
	v_writelane_b32 v187, s79, 15
	v_lshrrev_b32_e32 v188, 6, v196
	v_and_b32_e32 v189, 63, v196
	v_readfirstlane_b32 s73, v188
	v_lshrrev_b32_e32 v190, 2, v189
	v_bfe_u32 v191, v189, 4, 2
	v_and_b32_e32 v188, 3, v189
	v_xor_b32_e32 v188, v188, v191
	v_lshlrev_b32_e32 v188, 4, v188
	v_lshl_add_u32 v176, v190, 11, v188
	v_add_u32_e32 v177, 0x8000, v176
	v_lshl_add_u32 v178, v190, 6, v188
	v_and_b32_e32 v190, 31, v189
	v_lshrrev_b32_e32 v191, 5, v189
	v_bfe_u32 v188, v189, 2, 2
	v_xor_b32_e32 v188, v188, v191
	v_lshlrev_b32_e32 v188, 4, v188
	v_lshl_add_u32 v179, v190, 6, v188
	s_lshr_b32 s74, s73, 1
	s_lshl_b32 s74, s74, 12
	s_and_b32 s75, s73, 1
	s_lshl_b32 s75, s75, 13
	v_add_u32_e32 v181, s75, v179
	v_add_u32_e32 v179, s74, v179
	v_xor_b32_e32 v182, 32, v181
	v_xor_b32_e32 v180, 32, v179
	s_lshl_b32 s74, s73, 16
	s_add_u32 s64, s98, s74
	s_addc_u32 s65, s99, 0
	s_lshl_b32 s74, s73, 12
	s_add_u32 s66, s100, s74
	s_addc_u32 s67, s101, 0
	s_lshl_b32 s68, s73, 11
	s_lshl_b32 s69, s73, 12
	s_mov_b32 s70, 0
	s_mov_b32 s71, 0
	s_mov_b32 s72, 0
	s_waitcnt lgkmcnt(0)
	s_barrier
	s_mul_i32 s74, s70, 0x6000
	s_add_u32 s75, s74, s68
	s_mov_b32 m0, s75
	s_add_u32 s76, s74, 0x2000
	s_cmp_eq_u32 s70, 2
	s_cselect_b32 s76, 0x10000, s76
	global_load_lds_dwordx4 v176, s[64:65]
	s_add_u32 m0, s75, 0x400
	s_add_u32 s76, s76, s69
	global_load_lds_dwordx4 v177, s[64:65]
	s_mov_b32 m0, s76
	s_add_u32 s64, s64, 64
	s_addc_u32 s65, s65, 0
	global_load_lds_dwordx4 v178, s[66:67]
	global_load_lds_dwordx4 v178, s[66:67] offset:1024
	global_load_lds_dwordx4 v178, s[66:67] offset:2048
	global_load_lds_dwordx4 v178, s[66:67] offset:3072
	s_add_u32 s66, s66, 0x10000
	s_addc_u32 s67, s67, 0
	s_add_u32 s70, s70, 1
	s_cmp_eq_u32 s70, 3
	s_cselect_b32 s70, 0, s70
	s_mul_i32 s74, s70, 0x6000
	s_add_u32 s75, s74, s68
	s_mov_b32 m0, s75
	s_add_u32 s76, s74, 0x2000
	s_cmp_eq_u32 s70, 2
	s_cselect_b32 s76, 0x10000, s76
	global_load_lds_dwordx4 v176, s[64:65]
	s_add_u32 m0, s75, 0x400
	s_add_u32 s76, s76, s69
	global_load_lds_dwordx4 v177, s[64:65]
	s_mov_b32 m0, s76
	s_add_u32 s64, s64, 64
	s_addc_u32 s65, s65, 0
	global_load_lds_dwordx4 v178, s[66:67]
	global_load_lds_dwordx4 v178, s[66:67] offset:1024
	global_load_lds_dwordx4 v178, s[66:67] offset:2048
	global_load_lds_dwordx4 v178, s[66:67] offset:3072
	s_add_u32 s66, s66, 0x10000
	s_addc_u32 s67, s67, 0
	s_add_u32 s70, s70, 1
	s_cmp_eq_u32 s70, 3
	s_cselect_b32 s70, 0, s70
	s_cmp_lt_u32 s46, 0x100
	s_cbranch_scc1 .Lp17_nostag
	s_sleep 8

; #define GA_LOAD(pr_) do { _Pragma("unroll") for (int i = 0; i < 4; ++i) ra[i] = *(const u32x4*)(Ab + (i * 32) * lda + (pr_) * 64); } while (0)
; #define GB_LOAD(kt_) do { const bfr* bk_ = Bb + (kt_) * NB * 32; \
;     _Pragma("unroll") for (int i = 0; i < 4; ++i) rb[i] = *(const u32x4*)(bk_ + (i * 64) * 32); } while (0)
; #define G_STORE(kt_) do { bfr* as_ = S0 + ((kt_) & 1) * GSTAGE; bfr* bs_ = as_ + 128 * 40; \
;     if (apar == ((kt_) & 1)) { _Pragma("unroll") for (int i = 0; i < 4; ++i) *(u32x4*)(as_ + asoff + i * 32 * 40) = ra[i]; } \
;     _Pragma("unroll") for (int i = 0; i < 4; ++i) *(u32x4*)(bs_ + bsoff + i * 64 * 40) = rb[i]; } while (0)
; template <int lda>
; DI void gemm_mainloop(const bfr* __restrict__ A, const bfr* __restrict__ Bt, int NB, int K, int m0, int n0, char* smem, f32x16 (&acc)[2][4]) {
;     ...
;   u32x4 ra[4], rb[4];
;   const int nk = K >> 5;
;   const int arow = tid >> 3, ac8 = tid & 7, apar = ac8 >> 2;
;   const bfr* Ab = A + (m0 + arow) * lda + ac8 * 8;
;   const int asoff = arow * 40 + (ac8 & 3) * 8;
;   const int brow = tid >> 2, bc4 = tid & 3;
;   const bfr* Bb = Bt + (n0 + brow) * 32 + bc4 * 8;
;   const int bsoff = brow * 40 + bc4 * 8;
;     ...
;   GA_LOAD(0);
;   GB_LOAD(0);
;   G_STORE(0);
;   GB_LOAD(1);
;   __syncthreads();
; template <bool FIRST, bool HAS_H>
; DI void phase_gemm_resid(const Params& p, const bfr* A, const bfr* Wt, const float* gnext, float* ss, char* smem) {
;     ...
;   for (int t0 = blockIdx.x; t0 < 128 * 4; t0 += gridDim.x) {
;     const int t = ((gridDim.x & 7) == 0) ? xcd_tile(t0, 4) : t0;
;     const int mt = t >> 2, nt = t & 3, m0 = mt * 128, n0 = nt * 256;
;     f32x16 acc[2][4];
;     gemm_mainloop<1024>(A, Wt, 1024, 1024, m0, n0, smem, acc);
.LBB0_1721:
	s_lshl_b32 s5, s4, 5
	s_and_b32 s59, s5, 0xffffff80
	s_lshl_b32 s4, s4, 8
	s_and_b32 s58, s4, 0x300
	s_mov_b32 s60, 0
	s_mov_b64 s[16:17], 0
	s_lshl_b32 s98, s59, 11
	s_add_u32 s98, s6, s98
	s_addc_u32 s99, s7, 0
	s_lshl_b32 s100, s58, 6
	s_add_u32 s100, s2, s100
	s_addc_u32 s101, s3, 0
	v_writelane_b32 v188, s64, 0
	v_writelane_b32 v188, s65, 1
	v_writelane_b32 v188, s66, 2
	v_writelane_b32 v188, s67, 3
	v_writelane_b32 v188, s68, 4
	v_writelane_b32 v188, s69, 5
	v_writelane_b32 v188, s70, 6
	v_writelane_b32 v188, s71, 7
	v_writelane_b32 v188, s72, 8
	v_writelane_b32 v188, s73, 9
	v_writelane_b32 v188, s74, 10
	v_writelane_b32 v188, s75, 11
	v_writelane_b32 v188, s76, 12
	v_writelane_b32 v188, s77, 13
	v_writelane_b32 v188, s78, 14
	v_writelane_b32 v188, s79, 15
	v_lshrrev_b32_e32 v189, 6, v196
	v_and_b32_e32 v190, 63, v196
	v_readfirstlane_b32 s73, v189
	v_lshrrev_b32_e32 v191, 2, v190
	v_bfe_u32 v192, v190, 4, 2
	v_and_b32_e32 v189, 3, v190
	v_xor_b32_e32 v189, v189, v192
	v_lshlrev_b32_e32 v189, 4, v189
	v_lshl_add_u32 v176, v191, 11, v189
	v_add_u32_e32 v177, 0x8000, v176
	v_lshl_add_u32 v178, v191, 6, v189
	v_and_b32_e32 v191, 31, v190
	v_lshrrev_b32_e32 v192, 5, v190
	v_bfe_u32 v189, v190, 2, 2
	v_xor_b32_e32 v189, v189, v192
	v_lshlrev_b32_e32 v189, 4, v189
	v_lshl_add_u32 v179, v191, 6, v189
	s_lshr_b32 s74, s73, 1
	s_lshl_b32 s74, s74, 12
	s_and_b32 s75, s73, 1
	s_lshl_b32 s75, s75, 13
	v_add_u32_e32 v182, s75, v179
	v_add_u32_e32 v179, s74, v179
	v_xor_b32_e32 v183, 32, v182
	v_xor_b32_e32 v180, 32, v179
	s_lshl_b32 s74, s73, 16
	s_add_u32 s64, s98, s74
	s_addc_u32 s65, s99, 0
	s_lshl_b32 s74, s73, 12
	s_add_u32 s66, s100, s74
	s_addc_u32 s67, s101, 0
	s_lshl_b32 s68, s73, 11
	s_lshl_b32 s69, s73, 12
	s_mov_b32 s70, 0
	s_mov_b32 s71, 0
	s_mov_b32 s72, 0
	s_waitcnt lgkmcnt(0)
	s_barrier
	s_mul_i32 s74, s70, 0x6000
	s_add_u32 s75, s74, s68
	s_mov_b32 m0, s75
	s_add_u32 s76, s74, 0x2000
	s_cmp_eq_u32 s70, 2
	s_cselect_b32 s76, 0x10000, s76
	global_load_lds_dwordx4 v176, s[64:65]
	s_add_u32 m0, s75, 0x400
	s_add_u32 s76, s76, s69
	global_load_lds_dwordx4 v177, s[64:65]
	s_mov_b32 m0, s76
	s_add_u32 s64, s64, 64
	s_addc_u32 s65, s65, 0
	global_load_lds_dwordx4 v178, s[66:67]
	global_load_lds_dwordx4 v178, s[66:67] offset:1024
	global_load_lds_dwordx4 v178, s[66:67] offset:2048
	global_load_lds_dwordx4 v178, s[66:67] offset:3072
	s_add_u32 s66, s66, 0x10000
	s_addc_u32 s67, s67, 0
	s_add_u32 s70, s70, 1
	s_cmp_eq_u32 s70, 3
	s_cselect_b32 s70, 0, s70
	s_mul_i32 s74, s70, 0x6000
	s_add_u32 s75, s74, s68
	s_mov_b32 m0, s75
	s_add_u32 s76, s74, 0x2000
	s_cmp_eq_u32 s70, 2
	s_cselect_b32 s76, 0x10000, s76
	global_load_lds_dwordx4 v176, s[64:65]
	s_add_u32 m0, s75, 0x400
	s_add_u32 s76, s76, s69
	global_load_lds_dwordx4 v177, s[64:65]
	s_mov_b32 m0, s76
	s_add_u32 s64, s64, 64
	s_addc_u32 s65, s65, 0
	global_load_lds_dwordx4 v178, s[66:67]
	global_load_lds_dwordx4 v178, s[66:67] offset:1024
	global_load_lds_dwordx4 v178, s[66:67] offset:2048
	global_load_lds_dwordx4 v178, s[66:67] offset:3072
	s_add_u32 s66, s66, 0x10000
	s_addc_u32 s67, s67, 0
	s_add_u32 s70, s70, 1
	s_cmp_eq_u32 s70, 3
	s_cselect_b32 s70, 0, s70
	s_cmp_lt_u32 s46, 0x100
	s_cbranch_scc1 .Lp19_nostag
	s_sleep 8
